# static priority raise A/B: same as the previous variant but the raise is given to waves 0-3 instead of 4-7
# baseline (speedup 1.0000x reference)
.LBB0_2450:
	v_mov_b32_e32 v0, v1
	s_movk_i32 s2, 0xffc0
	v_mbcnt_lo_u32_b32 v0, -1, v0
	v_mbcnt_hi_u32_b32 v0, -1, v0
	v_add_u32_e32 v4, s33, v0
	s_nop 0
	v_readfirstlane_b32 s1, v4
	s_nop 1
	v_mov_b32_e32 v0, s1
	v_bfi_b32 v0, s2, v0, v4
	v_mul_hi_i32 v2, v0, s70
	v_lshrrev_b32_e32 v3, 31, v2
	v_ashrrev_i32_e32 v2, 2, v2
	v_add_u32_e32 v2, v2, v3
	v_lshlrev_b32_e32 v3, 1, v2
	v_mad_u64_u32 v[6:7], s[4:5], v2, s71, v[0:1]
	v_and_b32_e32 v3, 4, v3
	v_bfe_u32 v5, v2, 2, 2
	v_bitop3_b32 v5, v3, v6, v5 bitop3:0x36
	v_cmp_lt_i32_e32 vcc, 15, v5
	s_and_saveexec_b64 s[4:5], vcc
	s_xor_b64 s[4:5], exec, s[4:5]
	v_mul_lo_u32 v2, v2, s72
	v_add_u32_e32 v6, s97, v2
	s_or_saveexec_b64 s[4:5], s[4:5]
	s_add_i32 s91, s90, s95
	s_lshl_b32 s2, s91, 19
	s_add_i32 s2, s2, s11
	s_add_i32 s8, s2, 0x639ff300
	v_mov_b32_e32 v3, 1
	s_xor_b64 exec, exec, s[4:5]
	v_lshl_add_u32 v6, v2, 8, s8
	v_mov_b32_e32 v3, 0
	s_or_b64 exec, exec, s[4:5]
	v_add_u32_e32 v2, 0x200, v0
	v_mul_hi_i32 v7, v2, s70
	v_lshrrev_b32_e32 v8, 31, v7
	v_ashrrev_i32_e32 v7, 2, v7
	v_add_u32_e32 v9, v7, v8
	v_lshlrev_b32_e32 v7, 1, v9
	v_mad_u64_u32 v[10:11], s[4:5], v9, s71, v[2:3]
	v_and_b32_e32 v7, 4, v7
	v_bfe_u32 v8, v9, 2, 2
	v_bitop3_b32 v7, v7, v10, v8 bitop3:0x36
	v_cmp_lt_i32_e32 vcc, 15, v7
	s_and_saveexec_b64 s[4:5], vcc
	s_xor_b64 s[4:5], exec, s[4:5]
	v_mul_lo_u32 v8, v9, s72
	v_add_u32_e32 v8, s97, v8
	v_or_b32_e32 v3, 2, v3
	s_andn2_saveexec_b64 s[4:5], s[4:5]
	v_lshl_add_u32 v8, v9, 8, s8
	s_or_b64 exec, exec, s[4:5]
	v_add_u32_e32 v10, 0x400, v0
	v_mul_hi_i32 v9, v10, s70
	v_lshrrev_b32_e32 v11, 31, v9
	v_ashrrev_i32_e32 v9, 2, v9
	v_add_u32_e32 v11, v9, v11
	v_lshlrev_b32_e32 v9, 1, v11
	v_mad_u64_u32 v[12:13], s[4:5], v11, s71, v[10:11]
	v_and_b32_e32 v9, 4, v9
	v_bfe_u32 v10, v11, 2, 2
	v_bitop3_b32 v9, v9, v12, v10 bitop3:0x36
	v_cmp_lt_i32_e32 vcc, 15, v9
	s_and_saveexec_b64 s[4:5], vcc
	s_xor_b64 s[4:5], exec, s[4:5]
	v_mul_lo_u32 v10, v11, s72
	v_add_u32_e32 v10, s97, v10
	v_or_b32_e32 v3, 4, v3
	s_andn2_saveexec_b64 s[4:5], s[4:5]
	v_lshl_add_u32 v10, v11, 8, s8
	s_or_b64 exec, exec, s[4:5]
	v_ashrrev_i32_e32 v0, 4, v0
	v_lshl_add_u32 v145, v7, 4, v8
	v_lshlrev_b32_e32 v7, 2, v0
	v_lshl_add_u32 v148, v5, 4, v6
	v_and_b32_e32 v6, 15, v4
	v_and_b32_e32 v7, 12, v7
	v_bfe_u32 v8, v0, 2, 2
	v_bitop3_b32 v7, v7, v6, v8 bitop3:0x36
	v_ashrrev_i32_e32 v2, 4, v2
	v_lshl_add_u32 v149, v9, 4, v10
	v_lshlrev_b32_e32 v9, 4, v7
	v_lshlrev_b32_e32 v7, 2, v2
	s_bitcmp0_b32 s90, 0
	v_and_b32_e32 v7, 12, v7
	v_bfe_u32 v10, v2, 2, 2
	s_cselect_b32 s4, s85, s10
	s_ashr_i32 s5, s1, 6
	s_add_i32 s2, s2, 0x679ff300
	v_lshlrev_b32_e32 v8, 8, v0
	v_bitop3_b32 v6, v7, v6, v10 bitop3:0x36
	v_lshlrev_b32_e32 v2, 8, v2
	v_add_u32_e32 v0, s2, v8
	v_lshlrev_b32_e32 v10, 4, v6
	v_add_u32_e32 v6, s2, v2
	s_lshl_b32 s2, s5, 10
	s_add_i32 s49, s2, 0
	s_waitcnt lgkmcnt(0)
	s_barrier
	s_mov_b32 m0, s49
	s_add_i32 s93, s49, 0x2000
	s_lshl_b32 s1, s5, 5
	s_lshl_b32 s48, s4, 2
	s_lshl_b32 s4, s4, 8
	global_load_lds_dwordx4 v148, s[82:83]
	s_mov_b32 m0, s93
	s_add_i32 s74, s49, 0x4000
	s_add_i32 s1, s1, s4
	global_load_lds_dwordx4 v145, s[82:83]
	s_mov_b32 m0, s74
	s_add_i32 s75, s49, 0xc000
	s_add_i32 s48, s48, 4
	v_or_b32_e32 v0, v9, v0
	global_load_lds_dwordx4 v149, s[82:83]
	s_mov_b32 m0, s75
	s_add_i32 s76, s49, 0xe000
	s_ashr_i32 s2, s1, 31
	v_and_b32_e32 v5, 31, v4
	v_or_b32_e32 v6, v10, v6
	global_load_lds_dwordx4 v0, s[82:83]
	s_mov_b32 m0, s76
	s_add_u32 s4, s1, s96
	global_load_lds_dwordx4 v6, s[82:83]
	v_or_b32_e32 v146, s4, v5
	v_mov_b64_e32 v[6:7], s[44:45]
	s_movk_i32 s4, 0x1800
	v_mad_u64_u32 v[6:7], s[4:5], v146, s4, v[6:7]
	s_addc_u32 s2, s2, 0
	v_lshrrev_b32_e32 v0, 2, v4
	s_mul_i32 s4, s91, 0xc0
	v_and_b32_e32 v144, 8, v0
	v_mad_i32_i24 v7, s2, v158, v7
	s_ashr_i32 s5, s4, 31
	v_lshl_add_u64 v[6:7], s[4:5], 1, v[6:7]
	v_lshlrev_b32_e32 v0, 1, v144
	v_lshl_add_u64 v[6:7], v[6:7], 0, v[0:1]
	global_load_dwordx4 v[96:99], v[6:7], off offset:352
	global_load_dwordx4 v[100:103], v[6:7], off offset:320
	global_load_dwordx4 v[104:107], v[6:7], off offset:288
	global_load_dwordx4 v[108:111], v[6:7], off offset:256
	global_load_dwordx4 v[112:115], v[6:7], off offset:224
	global_load_dwordx4 v[116:119], v[6:7], off offset:192
	global_load_dwordx4 v[120:123], v[6:7], off offset:160
	global_load_dwordx4 v[124:127], v[6:7], off offset:128
	global_load_dwordx4 v[128:131], v[6:7], off offset:96
	global_load_dwordx4 v[132:135], v[6:7], off offset:64
	global_load_dwordx4 v[136:139], v[6:7], off offset:32
	global_load_dwordx4 v[140:143], v[6:7], off
	v_and_b32_e32 v11, 63, v4
	v_lshlrev_b32_e32 v7, 1, v11
	v_lshrrev_b32_e32 v0, 5, v11
	v_bfe_u32 v6, v4, 2, 2
	v_and_b32_e32 v7, 4, v7
	v_or_b32_e32 v17, 2, v0
	v_bitop3_b32 v20, v7, v0, v6 bitop3:0x36
	v_lshlrev_b32_e32 v152, 4, v20
	v_bitop3_b32 v20, v7, v17, v6 bitop3:0x36
	v_lshlrev_b32_e32 v153, 4, v20
	v_or_b32_e32 v20, 4, v0
	v_bitop3_b32 v20, v7, v20, v6 bitop3:0x36
	v_lshlrev_b32_e32 v154, 4, v20
	v_or_b32_e32 v20, 6, v0
	v_bitop3_b32 v20, v7, v20, v6 bitop3:0x36
	v_lshlrev_b32_e32 v155, 4, v20
	v_or_b32_e32 v20, 8, v0
	v_bitop3_b32 v20, v7, v20, v6 bitop3:0x36
	v_lshlrev_b32_e32 v156, 4, v20
	v_or_b32_e32 v20, 10, v0
	v_bitop3_b32 v20, v7, v20, v6 bitop3:0x36
	v_lshlrev_b32_e32 v157, 4, v20
	v_or_b32_e32 v20, 12, v0
	v_bitop3_b32 v20, v7, v20, v6 bitop3:0x36
	v_lshlrev_b32_e32 v164, 4, v20
	v_or_b32_e32 v20, 14, v0
	v_bitop3_b32 v20, v7, v20, v6 bitop3:0x36
	v_lshlrev_b32_e32 v165, 4, v20
	v_or_b32_e32 v20, 16, v0
	v_bitop3_b32 v20, v7, v20, v6 bitop3:0x36
	v_lshlrev_b32_e32 v166, 4, v20
	v_or_b32_e32 v20, 18, v0
	v_bitop3_b32 v20, v7, v20, v6 bitop3:0x36
	v_lshlrev_b32_e32 v167, 4, v20
	v_or_b32_e32 v20, 20, v0
	v_bitop3_b32 v20, v7, v20, v6 bitop3:0x36
	v_lshlrev_b32_e32 v168, 4, v20
	v_or_b32_e32 v20, 22, v0
	v_lshlrev_b32_e32 v12, 2, v0
	v_bitop3_b32 v7, v7, v20, v6 bitop3:0x36
	v_lshlrev_b32_e32 v169, 4, v7
	v_or_b32_e32 v7, 2, v12
	v_cmp_gt_u32_e64 s[14:15], v7, v5
	v_or_b32_e32 v7, 3, v12
	v_cmp_gt_u32_e64 s[16:17], v7, v5
	v_or_b32_e32 v7, 9, v12
	v_cmp_gt_u32_e64 s[20:21], v7, v5
	v_or_b32_e32 v7, 10, v12
	v_cmp_gt_u32_e64 s[22:23], v7, v5
	v_or_b32_e32 v7, 11, v12
	v_cmp_gt_u32_e64 s[24:25], v7, v5
	v_or_b32_e32 v7, 17, v12
	v_cmp_gt_u32_e64 s[28:29], v7, v5
	v_or_b32_e32 v7, 18, v12
	v_cmp_gt_u32_e64 s[30:31], v7, v5
	v_or_b32_e32 v7, 19, v12
	v_cmp_gt_u32_e64 s[34:35], v7, v5
	v_or_b32_e32 v7, 24, v12
	v_cmp_gt_u32_e64 s[36:37], v7, v5
	v_or_b32_e32 v7, 25, v12
	v_lshlrev_b32_e32 v13, 2, v11
	v_cmp_gt_u32_e64 s[38:39], v7, v5
	v_or_b32_e32 v7, 26, v12
	v_xor_b32_e32 v150, 0x80, v13
	v_lshrrev_b32_e32 v13, 3, v4
	v_bfe_u32 v14, v4, 1, 1
	v_or_b32_e32 v15, 16, v12
	v_or_b32_e32 v18, 8, v12
	v_cmp_gt_u32_e64 s[40:41], v7, v5
	v_or_b32_e32 v7, 27, v12
	v_and_b32_e32 v4, 12, v4
	v_and_or_b32 v13, v13, 2, v14
	v_lshlrev_b32_e32 v14, 3, v11
	v_mad_u32_u24 v151, v5, s73, 0
	v_cmp_gt_u32_e64 s[8:9], v12, v5
	v_cmp_lt_u32_e64 s[12:13], v12, v5
	v_cmp_gt_u32_e64 s[18:19], v18, v5
	v_cmp_gt_u32_e64 s[26:27], v15, v5
	v_cmp_gt_u32_e64 s[42:43], v7, v5
	v_or_b32_e32 v5, v12, v6
	v_or_b32_e32 v7, v0, v4
	v_and_b32_e32 v16, 8, v14
	v_lshlrev_b32_e32 v14, 2, v6
	v_lshrrev_b32_e32 v19, 2, v18
	v_lshlrev_b32_e32 v5, 8, v5
	v_or_b32_e32 v26, 4, v13
	v_bitop3_b32 v27, v13, v7, 4 bitop3:0x36
	v_or_b32_e32 v31, 8, v13
	v_bitop3_b32 v32, v13, v7, 8 bitop3:0x36
	v_or_b32_e32 v36, 12, v13
	v_bitop3_b32 v7, v13, v7, 12 bitop3:0x36
	v_or_b32_e32 v15, v15, v6
	v_bitop3_b32 v4, v0, v13, v4 bitop3:0x36
	v_add_u32_e32 v20, 0, v5
	v_or_b32_e32 v22, v18, v6
	v_bitop3_b32 v23, v19, v13, v14 bitop3:0x36
	v_bitop3_b32 v29, v19, v26, v14 bitop3:0x36
	v_bitop3_b32 v34, v19, v31, v14 bitop3:0x36
	v_lshlrev_b32_e32 v7, 4, v7
	v_bitop3_b32 v19, v19, v36, v14 bitop3:0x36
	v_bitop3_b32 v38, v14, v13, v0 bitop3:0x36
	v_lshlrev_b32_e32 v15, 8, v15
	v_bitop3_b32 v13, v14, v13, v17 bitop3:0x36
	v_bitop3_b32 v42, v14, v26, v0 bitop3:0x36
	v_bitop3_b32 v26, v14, v26, v17 bitop3:0x36
	v_bitop3_b32 v45, v14, v31, v0 bitop3:0x36
	v_bitop3_b32 v31, v14, v31, v17 bitop3:0x36
	v_bitop3_b32 v0, v14, v36, v0 bitop3:0x36
	v_bitop3_b32 v14, v14, v36, v17 bitop3:0x36
	v_or_b32_e32 v11, 32, v11
	v_or_b32_e32 v6, 32, v6
	v_add_u32_e32 v5, s62, v5
	v_lshlrev_b32_e32 v4, 4, v4
	v_lshlrev_b32_e32 v27, 4, v27
	v_lshlrev_b32_e32 v32, 4, v32
	v_add_u32_e32 v37, v20, v7
	v_lshlrev_b32_e32 v19, 4, v19
	v_add_u32_e32 v39, 0, v15
	v_lshlrev_b32_e32 v38, 4, v38
	v_lshlrev_b32_e32 v13, 4, v13
	v_lshlrev_b32_e32 v42, 4, v42
	v_lshlrev_b32_e32 v26, 4, v26
	v_lshlrev_b32_e32 v45, 4, v45
	v_lshlrev_b32_e32 v31, 4, v31
	v_lshlrev_b32_e32 v0, 4, v0
	v_lshlrev_b32_e32 v14, 4, v14
	v_mad_u32_u24 v170, v11, s73, 0
	v_or_b32_e32 v11, v6, v12
	v_add_u32_e32 v61, v5, v7
	v_add_u32_e32 v7, s62, v15
	v_add_u32_e32 v21, v20, v4
	v_add_u32_e32 v28, v20, v27
	v_add_u32_e32 v33, v20, v32
	v_add_u32_e32 v40, v39, v38
	v_add_u32_e32 v41, v20, v13
	v_add_u32_e32 v43, v39, v42
	v_add_u32_e32 v44, v20, v26
	v_add_u32_e32 v46, v39, v45
	v_add_u32_e32 v47, v20, v31
	v_add_u32_e32 v39, v39, v0
	v_add_u32_e32 v17, v20, v14
	v_lshlrev_b32_e32 v11, 8, v11
	v_or_b32_e32 v6, v18, v6
	v_add_u32_e32 v52, v20, v19
	v_add_u32_e32 v53, v20, v38
	v_add_u32_e32 v54, v20, v42
	v_add_u32_e32 v55, v20, v45
	v_add_u32_e32 v20, v20, v0
	v_add_u32_e32 v67, v7, v0
	v_add_u32_e32 v70, v5, v0
	v_and_b32_e32 v0, 1, v3
	v_lshlrev_b32_e32 v22, 8, v22
	v_add_u32_e32 v12, 0, v11
	v_lshlrev_b32_e32 v6, 8, v6
	v_add_u32_e32 v63, v7, v38
	v_add_u32_e32 v65, v7, v42
	v_add_u32_e32 v66, v7, v45
	v_add_u32_e32 v7, s62, v11
	v_cmp_eq_u32_e32 vcc, 0, v0
	v_and_b32_e32 v0, 2, v3
	v_add_u32_e32 v24, 0, v22
	v_lshlrev_b32_e32 v23, 4, v23
	v_lshlrev_b32_e32 v29, 4, v29
	v_lshlrev_b32_e32 v34, 4, v34
	v_add_u32_e32 v36, v12, v4
	v_add_u32_e32 v18, 0, v6
	v_add_u32_e32 v49, v12, v27
	v_add_u32_e32 v51, v12, v32
	v_add_u32_e32 v56, v5, v4
	v_add_u32_e32 v12, s62, v22
	v_add_u32_e32 v69, v7, v4
	v_add_u32_e32 v4, s62, v6
	v_cndmask_b32_e32 v171, v159, v160, vcc
	v_cmp_eq_u32_e32 vcc, 0, v0
	v_and_b32_e32 v0, 4, v3
	v_add_u32_e32 v25, v24, v23
	v_add_u32_e32 v30, v24, v29
	v_add_u32_e32 v35, v24, v34
	v_add_u32_e32 v24, v24, v19
	v_add_u32_e32 v48, v18, v23
	v_add_u32_e32 v50, v18, v29
	v_add_u32_e32 v18, v18, v34
	v_add_u32_e32 v22, v12, v23
	v_add_u32_e32 v57, v5, v27
	v_add_u32_e32 v58, v12, v29
	v_add_u32_e32 v59, v5, v32
	v_add_u32_e32 v60, v12, v34
	v_add_u32_e32 v62, v12, v19
	v_add_u32_e32 v64, v5, v13
	v_add_u32_e32 v26, v5, v26
	v_add_u32_e32 v31, v5, v31
	v_add_u32_e32 v68, v5, v14
	v_add_u32_e32 v23, v4, v23
	v_add_u32_e32 v27, v7, v27
	v_add_u32_e32 v29, v4, v29
	v_add_u32_e32 v32, v7, v32
	v_add_u32_e32 v34, v4, v34
	v_add_u32_e32 v19, v5, v19
	v_add_u32_e32 v38, v5, v38
	v_add_u32_e32 v42, v5, v42
	v_add_u32_e32 v45, v5, v45
	v_cndmask_b32_e32 v172, v159, v160, vcc
	v_cmp_eq_u32_e32 vcc, 0, v0
	v_mov_b32_e32 v14, v1
	v_mov_b32_e32 v15, v1
	v_cndmask_b32_e32 v173, v159, v160, vcc
	v_or_b32_e32 v177, v2, v10
	v_or_b32_e32 v178, v8, v9
	v_mov_b32_e32 v0, v1
	v_mov_b32_e32 v2, v1
	v_mov_b32_e32 v3, v1
	v_mov_b32_e32 v4, v1
	v_mov_b32_e32 v5, v1
	v_mov_b32_e32 v6, v1
	v_mov_b32_e32 v7, v1
	v_mov_b32_e32 v8, v1
	v_mov_b32_e32 v9, v1
	v_mov_b32_e32 v10, v1
	v_mov_b32_e32 v11, v1
	v_mov_b32_e32 v12, v1
	v_mov_b32_e32 v13, v1
	v_add_u32_e32 v180, v21, v16
	v_add_u32_e32 v181, v25, v16
	v_add_u32_e32 v182, v28, v16
	v_add_u32_e32 v183, v30, v16
	v_add_u32_e32 v184, v33, v16
	v_add_u32_e32 v185, v35, v16
	v_add_u32_e32 v186, v24, v16
	v_add_u32_e32 v187, v40, v16
	v_add_u32_e32 v188, v43, v16
	v_add_u32_e32 v189, v46, v16
	v_add_u32_e32 v190, v39, v16
	v_add_u32_e32 v191, v36, v16
	v_add_u32_e32 v235, v48, v16
	v_add_u32_e32 v252, v49, v16
	v_add_u32_e32 v253, v50, v16
	v_add_u32_e32 v254, v51, v16
	v_add_u32_e32 v196, v18, v16
	v_add_u32_e32 v197, v52, v16
	v_add_u32_e32 v198, v53, v16
	v_add_u32_e32 v199, v54, v16
	v_add_u32_e32 v200, v55, v16
	v_add_u32_e32 v201, v20, v16
	v_add_u32_e32 v202, v56, v16
	v_add_u32_e32 v203, v22, v16
	v_add_u32_e32 v204, v57, v16
	v_add_u32_e32 v205, v58, v16
	v_add_u32_e32 v206, v59, v16
	v_add_u32_e32 v207, v60, v16
	v_add_u32_e32 v208, v62, v16
	v_add_u32_e32 v209, v63, v16
	v_add_u32_e32 v210, v65, v16
	v_add_u32_e32 v211, v66, v16
	v_add_u32_e32 v212, v67, v16
	v_add_u32_e32 v213, v69, v16
	v_add_u32_e32 v214, v23, v16
	v_add_u32_e32 v215, v27, v16
	v_add_u32_e32 v216, v29, v16
	v_add_u32_e32 v217, v32, v16
	v_add_u32_e32 v218, v34, v16
	v_add_u32_e32 v219, v19, v16
	v_add_u32_e32 v220, v38, v16
	v_add_u32_e32 v221, v42, v16
	v_add_u32_e32 v222, v45, v16
	v_add_u32_e32 v223, v70, v16
	v_add_u32_e32 v224, v37, v16
	v_add_u32_e32 v225, v41, v16
	v_add_u32_e32 v226, v44, v16
	v_add_u32_e32 v227, v47, v16
	v_add_u32_e32 v228, v17, v16
	v_add_u32_e32 v229, v61, v16
	v_add_u32_e32 v230, v64, v16
	v_add_u32_e32 v231, v26, v16
	v_add_u32_e32 v232, v31, v16
	v_add_u32_e32 v233, v68, v16
	v_mov_b64_e32 v[30:31], v[14:15]
	v_mov_b64_e32 v[46:47], v[14:15]
	v_mov_b64_e32 v[62:63], v[14:15]
	v_mov_b64_e32 v[78:79], v[14:15]
	s_mov_b32 s92, 2
	v_mov_b32_e32 v147, s2
	s_or_b32 s46, s1, 31
	v_lshlrev_b32_e32 v174, 1, v171
	v_lshlrev_b32_e32 v175, 1, v172
	v_lshlrev_b32_e32 v176, 1, v173
	s_sub_i32 s2, 0, s1
	s_sub_i32 s47, 32, s1
	s_sub_i32 s50, 64, s1
	v_mov_b32_e32 v234, 0xf149f2ca
	v_mov_b32_e32 v179, 0
	s_movk_i32 s51, 0x60
	s_mov_b32 s1, s87
	v_mov_b64_e32 v[28:29], v[12:13]
	v_mov_b64_e32 v[26:27], v[10:11]
	v_mov_b64_e32 v[24:25], v[8:9]
	v_mov_b64_e32 v[22:23], v[6:7]
	v_mov_b64_e32 v[20:21], v[4:5]
	v_mov_b64_e32 v[18:19], v[2:3]
	v_mov_b64_e32 v[16:17], v[0:1]
	v_mov_b64_e32 v[44:45], v[12:13]
	v_mov_b64_e32 v[42:43], v[10:11]
	v_mov_b64_e32 v[40:41], v[8:9]
	v_mov_b64_e32 v[38:39], v[6:7]
	v_mov_b64_e32 v[36:37], v[4:5]
	v_mov_b64_e32 v[34:35], v[2:3]
	v_mov_b64_e32 v[32:33], v[0:1]
	v_mov_b64_e32 v[60:61], v[12:13]
	v_mov_b64_e32 v[58:59], v[10:11]
	v_mov_b64_e32 v[56:57], v[8:9]
	v_mov_b64_e32 v[54:55], v[6:7]
	v_mov_b64_e32 v[52:53], v[4:5]
	v_mov_b64_e32 v[50:51], v[2:3]
	v_mov_b64_e32 v[48:49], v[0:1]
	v_mov_b64_e32 v[76:77], v[12:13]
	v_mov_b64_e32 v[74:75], v[10:11]
	v_mov_b64_e32 v[72:73], v[8:9]
	v_mov_b64_e32 v[70:71], v[6:7]
	v_mov_b64_e32 v[68:69], v[4:5]
	v_mov_b64_e32 v[66:67], v[2:3]
	v_mov_b64_e32 v[64:65], v[0:1]
	s_waitcnt vmcnt(0)
	s_cmp_ge_u32 s33, 0x100
	s_cbranch_scc1 .Lmy_prio_a2
	s_setprio 1

.LBB0_3761:
	v_mov_b32_e32 v0, v1
	s_movk_i32 s2, 0xffc0
	v_mbcnt_lo_u32_b32 v0, -1, v0
	v_mbcnt_hi_u32_b32 v0, -1, v0
	v_add_u32_e32 v4, s33, v0
	s_nop 0
	v_readfirstlane_b32 s1, v4
	s_nop 1
	v_mov_b32_e32 v0, s1
	v_bfi_b32 v0, s2, v0, v4
	v_mul_hi_i32 v2, v0, s97
	v_lshrrev_b32_e32 v3, 31, v2
	v_ashrrev_i32_e32 v2, 2, v2
	v_add_u32_e32 v2, v2, v3
	v_lshlrev_b32_e32 v3, 1, v2
	v_mad_u64_u32 v[6:7], s[4:5], v2, s56, v[0:1]
	v_and_b32_e32 v3, 4, v3
	v_bfe_u32 v5, v2, 2, 2
	v_bitop3_b32 v5, v3, v6, v5 bitop3:0x36
	v_cmp_lt_i32_e32 vcc, 15, v5
	s_and_saveexec_b64 s[4:5], vcc
	s_xor_b64 s[4:5], exec, s[4:5]
	v_mul_lo_u32 v2, v2, s57
	v_add_u32_e32 v6, s78, v2
	s_or_saveexec_b64 s[4:5], s[4:5]
	s_add_i32 s90, s87, s74
	s_lshl_b32 s2, s90, 19
	s_add_i32 s2, s2, s76
	s_add_i32 s8, s2, 0x639ff300
	v_mov_b32_e32 v3, 1
	s_xor_b64 exec, exec, s[4:5]
	v_lshl_add_u32 v6, v2, 8, s8
	v_mov_b32_e32 v3, 0
	s_or_b64 exec, exec, s[4:5]
	v_add_u32_e32 v2, 0x200, v0
	v_mul_hi_i32 v7, v2, s97
	v_lshrrev_b32_e32 v8, 31, v7
	v_ashrrev_i32_e32 v7, 2, v7
	v_add_u32_e32 v9, v7, v8
	v_lshlrev_b32_e32 v7, 1, v9
	v_mad_u64_u32 v[10:11], s[4:5], v9, s56, v[2:3]
	v_and_b32_e32 v7, 4, v7
	v_bfe_u32 v8, v9, 2, 2
	v_bitop3_b32 v7, v7, v10, v8 bitop3:0x36
	v_cmp_lt_i32_e32 vcc, 15, v7
	s_and_saveexec_b64 s[4:5], vcc
	s_xor_b64 s[4:5], exec, s[4:5]
	v_mul_lo_u32 v8, v9, s57
	v_add_u32_e32 v8, s78, v8
	v_or_b32_e32 v3, 2, v3
	s_andn2_saveexec_b64 s[4:5], s[4:5]
	v_lshl_add_u32 v8, v9, 8, s8
	s_or_b64 exec, exec, s[4:5]
	v_add_u32_e32 v10, 0x400, v0
	v_mul_hi_i32 v9, v10, s97
	v_lshrrev_b32_e32 v11, 31, v9
	v_ashrrev_i32_e32 v9, 2, v9
	v_add_u32_e32 v11, v9, v11
	v_lshlrev_b32_e32 v9, 1, v11
	v_mad_u64_u32 v[12:13], s[4:5], v11, s56, v[10:11]
	v_and_b32_e32 v9, 4, v9
	v_bfe_u32 v10, v11, 2, 2
	v_bitop3_b32 v9, v9, v12, v10 bitop3:0x36
	v_cmp_lt_i32_e32 vcc, 15, v9
	s_and_saveexec_b64 s[4:5], vcc
	s_xor_b64 s[4:5], exec, s[4:5]
	v_mul_lo_u32 v10, v11, s57
	v_add_u32_e32 v10, s78, v10
	v_or_b32_e32 v3, 4, v3
	s_andn2_saveexec_b64 s[4:5], s[4:5]
	v_lshl_add_u32 v10, v11, 8, s8
	s_or_b64 exec, exec, s[4:5]
	v_ashrrev_i32_e32 v0, 4, v0
	v_lshl_add_u32 v152, v7, 4, v8
	v_lshlrev_b32_e32 v7, 2, v0
	v_lshl_add_u32 v153, v5, 4, v6
	v_and_b32_e32 v6, 15, v4
	v_and_b32_e32 v7, 12, v7
	v_bfe_u32 v8, v0, 2, 2
	v_bitop3_b32 v7, v7, v6, v8 bitop3:0x36
	v_ashrrev_i32_e32 v2, 4, v2
	v_lshl_add_u32 v154, v9, 4, v10
	v_lshlrev_b32_e32 v9, 4, v7
	v_lshlrev_b32_e32 v7, 2, v2
	s_bitcmp0_b32 s87, 0
	v_and_b32_e32 v7, 12, v7
	v_bfe_u32 v10, v2, 2, 2
	s_cselect_b32 s4, s72, s75
	s_ashr_i32 s5, s1, 6
	s_add_i32 s2, s2, 0x679ff300
	v_lshlrev_b32_e32 v8, 8, v0
	v_bitop3_b32 v6, v7, v6, v10 bitop3:0x36
	v_lshlrev_b32_e32 v2, 8, v2
	v_add_u32_e32 v0, s2, v8
	v_lshlrev_b32_e32 v10, 4, v6
	v_add_u32_e32 v6, s2, v2
	s_lshl_b32 s2, s5, 10
	s_add_i32 s65, s2, 0
	s_waitcnt lgkmcnt(0)
	s_barrier
	s_mov_b32 m0, s65
	s_add_i32 s52, s65, 0x2000
	s_lshl_b32 s1, s5, 5
	s_lshl_b32 s64, s4, 2
	s_lshl_b32 s4, s4, 8
	global_load_lds_dwordx4 v153, s[82:83]
	s_mov_b32 m0, s52
	s_add_i32 s53, s65, 0x4000
	s_add_i32 s1, s1, s4
	global_load_lds_dwordx4 v152, s[82:83]
	s_mov_b32 m0, s53
	s_add_i32 s60, s65, 0xc000
	s_add_i32 s64, s64, 4
	v_or_b32_e32 v0, v9, v0
	global_load_lds_dwordx4 v154, s[82:83]
	s_mov_b32 m0, s60
	s_add_i32 s61, s65, 0xe000
	s_ashr_i32 s2, s1, 31
	v_and_b32_e32 v5, 31, v4
	v_or_b32_e32 v6, v10, v6
	global_load_lds_dwordx4 v0, s[82:83]
	s_mov_b32 m0, s61
	s_add_u32 s4, s1, s77
	global_load_lds_dwordx4 v6, s[82:83]
	v_or_b32_e32 v146, s4, v5
	v_mov_b64_e32 v[6:7], s[44:45]
	s_movk_i32 s4, 0x1800
	v_mad_u64_u32 v[6:7], s[4:5], v146, s4, v[6:7]
	s_addc_u32 s2, s2, 0
	v_lshrrev_b32_e32 v0, 2, v4
	s_mul_i32 s4, s90, 0xc0
	v_and_b32_e32 v144, 8, v0
	v_mad_i32_i24 v7, s2, v145, v7
	s_ashr_i32 s5, s4, 31
	v_lshl_add_u64 v[6:7], s[4:5], 1, v[6:7]
	v_lshlrev_b32_e32 v0, 1, v144
	v_lshl_add_u64 v[6:7], v[6:7], 0, v[0:1]
	global_load_dwordx4 v[96:99], v[6:7], off offset:352
	global_load_dwordx4 v[100:103], v[6:7], off offset:320
	global_load_dwordx4 v[104:107], v[6:7], off offset:288
	global_load_dwordx4 v[108:111], v[6:7], off offset:256
	global_load_dwordx4 v[112:115], v[6:7], off offset:224
	global_load_dwordx4 v[116:119], v[6:7], off offset:192
	global_load_dwordx4 v[120:123], v[6:7], off offset:160
	global_load_dwordx4 v[124:127], v[6:7], off offset:128
	global_load_dwordx4 v[128:131], v[6:7], off offset:96
	global_load_dwordx4 v[132:135], v[6:7], off offset:64
	global_load_dwordx4 v[136:139], v[6:7], off offset:32
	global_load_dwordx4 v[140:143], v[6:7], off
	v_and_b32_e32 v11, 63, v4
	v_lshlrev_b32_e32 v7, 1, v11
	v_lshrrev_b32_e32 v0, 5, v11
	v_bfe_u32 v6, v4, 2, 2
	v_and_b32_e32 v7, 4, v7
	v_or_b32_e32 v17, 2, v0
	v_bitop3_b32 v20, v7, v0, v6 bitop3:0x36
	v_lshlrev_b32_e32 v157, 4, v20
	v_bitop3_b32 v20, v7, v17, v6 bitop3:0x36
	v_lshlrev_b32_e32 v158, 4, v20
	v_or_b32_e32 v20, 4, v0
	v_bitop3_b32 v20, v7, v20, v6 bitop3:0x36
	v_lshlrev_b32_e32 v159, 4, v20
	v_or_b32_e32 v20, 6, v0
	v_bitop3_b32 v20, v7, v20, v6 bitop3:0x36
	v_lshlrev_b32_e32 v160, 4, v20
	v_or_b32_e32 v20, 8, v0
	v_bitop3_b32 v20, v7, v20, v6 bitop3:0x36
	v_lshlrev_b32_e32 v161, 4, v20
	v_or_b32_e32 v20, 10, v0
	v_bitop3_b32 v20, v7, v20, v6 bitop3:0x36
	v_lshlrev_b32_e32 v162, 4, v20
	v_or_b32_e32 v20, 12, v0
	v_bitop3_b32 v20, v7, v20, v6 bitop3:0x36
	v_lshlrev_b32_e32 v163, 4, v20
	v_or_b32_e32 v20, 14, v0
	v_bitop3_b32 v20, v7, v20, v6 bitop3:0x36
	v_lshlrev_b32_e32 v164, 4, v20
	v_or_b32_e32 v20, 16, v0
	v_bitop3_b32 v20, v7, v20, v6 bitop3:0x36
	v_lshlrev_b32_e32 v165, 4, v20
	v_or_b32_e32 v20, 18, v0
	v_bitop3_b32 v20, v7, v20, v6 bitop3:0x36
	v_lshlrev_b32_e32 v166, 4, v20
	v_or_b32_e32 v20, 20, v0
	v_bitop3_b32 v20, v7, v20, v6 bitop3:0x36
	v_lshlrev_b32_e32 v167, 4, v20
	v_or_b32_e32 v20, 22, v0
	v_lshlrev_b32_e32 v12, 2, v0
	v_bitop3_b32 v7, v7, v20, v6 bitop3:0x36
	v_lshlrev_b32_e32 v168, 4, v7
	v_or_b32_e32 v7, 2, v12
	v_cmp_gt_u32_e64 s[12:13], v7, v5
	v_or_b32_e32 v7, 3, v12
	v_cmp_gt_u32_e64 s[14:15], v7, v5
	v_or_b32_e32 v7, 9, v12
	v_cmp_gt_u32_e64 s[18:19], v7, v5
	v_or_b32_e32 v7, 10, v12
	v_cmp_gt_u32_e64 s[20:21], v7, v5
	v_or_b32_e32 v7, 11, v12
	v_cmp_gt_u32_e64 s[22:23], v7, v5
	v_or_b32_e32 v7, 17, v12
	v_cmp_gt_u32_e64 s[26:27], v7, v5
	v_or_b32_e32 v7, 18, v12
	v_cmp_gt_u32_e64 s[28:29], v7, v5
	v_or_b32_e32 v7, 19, v12
	v_cmp_gt_u32_e64 s[30:31], v7, v5
	v_or_b32_e32 v7, 24, v12
	v_cmp_gt_u32_e64 s[34:35], v7, v5
	v_or_b32_e32 v7, 25, v12
	v_lshlrev_b32_e32 v13, 2, v11
	v_cmp_gt_u32_e64 s[36:37], v7, v5
	v_or_b32_e32 v7, 26, v12
	v_xor_b32_e32 v155, 0x80, v13
	v_lshrrev_b32_e32 v13, 3, v4
	v_bfe_u32 v14, v4, 1, 1
	v_or_b32_e32 v15, 16, v12
	v_or_b32_e32 v18, 8, v12
	v_cmp_gt_u32_e64 s[38:39], v7, v5
	v_or_b32_e32 v7, 27, v12
	v_and_b32_e32 v4, 12, v4
	v_and_or_b32 v13, v13, 2, v14
	v_lshlrev_b32_e32 v14, 3, v11
	v_mad_u32_u24 v156, v5, s54, 0
	v_cmp_gt_u32_e64 s[8:9], v12, v5
	v_cmp_lt_u32_e64 s[10:11], v12, v5
	v_cmp_gt_u32_e64 s[16:17], v18, v5
	v_cmp_gt_u32_e64 s[24:25], v15, v5
	v_cmp_gt_u32_e64 s[40:41], v7, v5
	v_or_b32_e32 v5, v12, v6
	v_or_b32_e32 v7, v0, v4
	v_and_b32_e32 v16, 8, v14
	v_lshlrev_b32_e32 v14, 2, v6
	v_lshrrev_b32_e32 v19, 2, v18
	v_lshlrev_b32_e32 v5, 8, v5
	v_or_b32_e32 v26, 4, v13
	v_bitop3_b32 v27, v13, v7, 4 bitop3:0x36
	v_or_b32_e32 v31, 8, v13
	v_bitop3_b32 v32, v13, v7, 8 bitop3:0x36
	v_or_b32_e32 v36, 12, v13
	v_bitop3_b32 v7, v13, v7, 12 bitop3:0x36
	v_or_b32_e32 v15, v15, v6
	v_bitop3_b32 v4, v0, v13, v4 bitop3:0x36
	v_add_u32_e32 v20, 0, v5
	v_or_b32_e32 v22, v18, v6
	v_bitop3_b32 v23, v19, v13, v14 bitop3:0x36
	v_bitop3_b32 v29, v19, v26, v14 bitop3:0x36
	v_bitop3_b32 v34, v19, v31, v14 bitop3:0x36
	v_lshlrev_b32_e32 v7, 4, v7
	v_bitop3_b32 v19, v19, v36, v14 bitop3:0x36
	v_bitop3_b32 v38, v14, v13, v0 bitop3:0x36
	v_lshlrev_b32_e32 v15, 8, v15
	v_bitop3_b32 v13, v14, v13, v17 bitop3:0x36
	v_bitop3_b32 v42, v14, v26, v0 bitop3:0x36
	v_bitop3_b32 v26, v14, v26, v17 bitop3:0x36
	v_bitop3_b32 v45, v14, v31, v0 bitop3:0x36
	v_bitop3_b32 v31, v14, v31, v17 bitop3:0x36
	v_bitop3_b32 v0, v14, v36, v0 bitop3:0x36
	v_bitop3_b32 v14, v14, v36, v17 bitop3:0x36
	v_or_b32_e32 v11, 32, v11
	v_or_b32_e32 v6, 32, v6
	v_add_u32_e32 v5, s55, v5
	v_lshlrev_b32_e32 v4, 4, v4
	v_lshlrev_b32_e32 v27, 4, v27
	v_lshlrev_b32_e32 v32, 4, v32
	v_add_u32_e32 v37, v20, v7
	v_lshlrev_b32_e32 v19, 4, v19
	v_add_u32_e32 v39, 0, v15
	v_lshlrev_b32_e32 v38, 4, v38
	v_lshlrev_b32_e32 v13, 4, v13
	v_lshlrev_b32_e32 v42, 4, v42
	v_lshlrev_b32_e32 v26, 4, v26
	v_lshlrev_b32_e32 v45, 4, v45
	v_lshlrev_b32_e32 v31, 4, v31
	v_lshlrev_b32_e32 v0, 4, v0
	v_lshlrev_b32_e32 v14, 4, v14
	v_mad_u32_u24 v169, v11, s54, 0
	v_or_b32_e32 v11, v6, v12
	v_add_u32_e32 v61, v5, v7
	v_add_u32_e32 v7, s55, v15
	v_add_u32_e32 v21, v20, v4
	v_add_u32_e32 v28, v20, v27
	v_add_u32_e32 v33, v20, v32
	v_add_u32_e32 v40, v39, v38
	v_add_u32_e32 v41, v20, v13
	v_add_u32_e32 v43, v39, v42
	v_add_u32_e32 v44, v20, v26
	v_add_u32_e32 v46, v39, v45
	v_add_u32_e32 v47, v20, v31
	v_add_u32_e32 v39, v39, v0
	v_add_u32_e32 v17, v20, v14
	v_lshlrev_b32_e32 v11, 8, v11
	v_or_b32_e32 v6, v18, v6
	v_add_u32_e32 v52, v20, v19
	v_add_u32_e32 v53, v20, v38
	v_add_u32_e32 v54, v20, v42
	v_add_u32_e32 v55, v20, v45
	v_add_u32_e32 v20, v20, v0
	v_add_u32_e32 v67, v7, v0
	v_add_u32_e32 v70, v5, v0
	v_and_b32_e32 v0, 1, v3
	v_lshlrev_b32_e32 v22, 8, v22
	v_add_u32_e32 v12, 0, v11
	v_lshlrev_b32_e32 v6, 8, v6
	v_add_u32_e32 v63, v7, v38
	v_add_u32_e32 v65, v7, v42
	v_add_u32_e32 v66, v7, v45
	v_add_u32_e32 v7, s55, v11
	v_cmp_eq_u32_e32 vcc, 0, v0
	v_and_b32_e32 v0, 2, v3
	v_add_u32_e32 v24, 0, v22
	v_lshlrev_b32_e32 v23, 4, v23
	v_lshlrev_b32_e32 v29, 4, v29
	v_lshlrev_b32_e32 v34, 4, v34
	v_add_u32_e32 v36, v12, v4
	v_add_u32_e32 v18, 0, v6
	v_add_u32_e32 v49, v12, v27
	v_add_u32_e32 v51, v12, v32
	v_add_u32_e32 v56, v5, v4
	v_add_u32_e32 v12, s55, v22
	v_add_u32_e32 v69, v7, v4
	v_add_u32_e32 v4, s55, v6
	v_cndmask_b32_e32 v170, v148, v149, vcc
	v_cmp_eq_u32_e32 vcc, 0, v0
	v_and_b32_e32 v0, 4, v3
	v_add_u32_e32 v25, v24, v23
	v_add_u32_e32 v30, v24, v29
	v_add_u32_e32 v35, v24, v34
	v_add_u32_e32 v24, v24, v19
	v_add_u32_e32 v48, v18, v23
	v_add_u32_e32 v50, v18, v29
	v_add_u32_e32 v18, v18, v34
	v_add_u32_e32 v22, v12, v23
	v_add_u32_e32 v57, v5, v27
	v_add_u32_e32 v58, v12, v29
	v_add_u32_e32 v59, v5, v32
	v_add_u32_e32 v60, v12, v34
	v_add_u32_e32 v62, v12, v19
	v_add_u32_e32 v64, v5, v13
	v_add_u32_e32 v26, v5, v26
	v_add_u32_e32 v31, v5, v31
	v_add_u32_e32 v68, v5, v14
	v_add_u32_e32 v23, v4, v23
	v_add_u32_e32 v27, v7, v27
	v_add_u32_e32 v29, v4, v29
	v_add_u32_e32 v32, v7, v32
	v_add_u32_e32 v34, v4, v34
	v_add_u32_e32 v19, v5, v19
	v_add_u32_e32 v38, v5, v38
	v_add_u32_e32 v42, v5, v42
	v_add_u32_e32 v45, v5, v45
	v_cndmask_b32_e32 v171, v148, v149, vcc
	v_cmp_eq_u32_e32 vcc, 0, v0
	v_mov_b32_e32 v14, v1
	v_mov_b32_e32 v15, v1
	v_cndmask_b32_e32 v172, v148, v149, vcc
	v_or_b32_e32 v176, v2, v10
	v_or_b32_e32 v177, v8, v9
	v_mov_b32_e32 v0, v1
	v_mov_b32_e32 v2, v1
	v_mov_b32_e32 v3, v1
	v_mov_b32_e32 v4, v1
	v_mov_b32_e32 v5, v1
	v_mov_b32_e32 v6, v1
	v_mov_b32_e32 v7, v1
	v_mov_b32_e32 v8, v1
	v_mov_b32_e32 v9, v1
	v_mov_b32_e32 v10, v1
	v_mov_b32_e32 v11, v1
	v_mov_b32_e32 v12, v1
	v_mov_b32_e32 v13, v1
	v_add_u32_e32 v179, v21, v16
	v_add_u32_e32 v180, v25, v16
	v_add_u32_e32 v181, v28, v16
	v_add_u32_e32 v182, v30, v16
	v_add_u32_e32 v183, v33, v16
	v_add_u32_e32 v184, v35, v16
	v_add_u32_e32 v185, v24, v16
	v_add_u32_e32 v186, v40, v16
	v_add_u32_e32 v187, v43, v16
	v_add_u32_e32 v188, v46, v16
	v_add_u32_e32 v189, v39, v16
	v_add_u32_e32 v190, v36, v16
	v_add_u32_e32 v191, v48, v16
	v_add_u32_e32 v192, v49, v16
	v_add_u32_e32 v193, v50, v16
	v_add_u32_e32 v194, v51, v16
	v_add_u32_e32 v195, v18, v16
	v_add_u32_e32 v196, v52, v16
	v_add_u32_e32 v197, v53, v16
	v_add_u32_e32 v198, v54, v16
	v_add_u32_e32 v199, v55, v16
	v_add_u32_e32 v200, v20, v16
	v_add_u32_e32 v201, v56, v16
	v_add_u32_e32 v202, v22, v16
	v_add_u32_e32 v203, v57, v16
	v_add_u32_e32 v204, v58, v16
	v_add_u32_e32 v205, v59, v16
	v_add_u32_e32 v206, v60, v16
	v_add_u32_e32 v207, v62, v16
	v_add_u32_e32 v208, v63, v16
	v_add_u32_e32 v209, v65, v16
	v_add_u32_e32 v210, v66, v16
	v_add_u32_e32 v211, v67, v16
	v_add_u32_e32 v212, v69, v16
	v_add_u32_e32 v213, v23, v16
	v_add_u32_e32 v214, v27, v16
	v_add_u32_e32 v215, v29, v16
	v_add_u32_e32 v216, v32, v16
	v_add_u32_e32 v217, v34, v16
	v_add_u32_e32 v218, v19, v16
	v_add_u32_e32 v219, v38, v16
	v_add_u32_e32 v220, v42, v16
	v_add_u32_e32 v221, v45, v16
	v_add_u32_e32 v222, v70, v16
	v_add_u32_e32 v223, v37, v16
	v_add_u32_e32 v224, v41, v16
	v_add_u32_e32 v225, v44, v16
	v_add_u32_e32 v226, v47, v16
	v_add_u32_e32 v227, v17, v16
	s_waitcnt vmcnt(0)
	v_add_u32_e32 v228, v61, v16
	v_add_u32_e32 v229, v64, v16
	v_add_u32_e32 v230, v26, v16
	v_add_u32_e32 v231, v31, v16
	v_add_u32_e32 v232, v68, v16
	v_mov_b64_e32 v[30:31], v[14:15]
	v_mov_b64_e32 v[46:47], v[14:15]
	v_mov_b64_e32 v[62:63], v[14:15]
	v_mov_b64_e32 v[78:79], v[14:15]
	s_mov_b32 s91, 2
	v_mov_b32_e32 v147, s2
	s_or_b32 s88, s1, 31
	v_lshlrev_b32_e32 v173, 1, v170
	v_lshlrev_b32_e32 v174, 1, v171
	v_lshlrev_b32_e32 v175, 1, v172
	s_sub_i32 s2, 0, s1
	s_sub_i32 s89, 32, s1
	s_sub_i32 s66, 64, s1
	v_mov_b32_e32 v233, 0xf149f2ca
	v_mov_b32_e32 v178, 0
	s_movk_i32 s67, 0x60
	s_mov_b32 s1, s86
	v_mov_b64_e32 v[28:29], v[12:13]
	v_mov_b64_e32 v[26:27], v[10:11]
	v_mov_b64_e32 v[24:25], v[8:9]
	v_mov_b64_e32 v[22:23], v[6:7]
	v_mov_b64_e32 v[20:21], v[4:5]
	v_mov_b64_e32 v[18:19], v[2:3]
	v_mov_b64_e32 v[16:17], v[0:1]
	v_mov_b64_e32 v[44:45], v[12:13]
	v_mov_b64_e32 v[42:43], v[10:11]
	v_mov_b64_e32 v[40:41], v[8:9]
	v_mov_b64_e32 v[38:39], v[6:7]
	v_mov_b64_e32 v[36:37], v[4:5]
	v_mov_b64_e32 v[34:35], v[2:3]
	v_mov_b64_e32 v[32:33], v[0:1]
	v_mov_b64_e32 v[60:61], v[12:13]
	v_mov_b64_e32 v[58:59], v[10:11]
	v_mov_b64_e32 v[56:57], v[8:9]
	v_mov_b64_e32 v[54:55], v[6:7]
	v_mov_b64_e32 v[52:53], v[4:5]
	v_mov_b64_e32 v[50:51], v[2:3]
	v_mov_b64_e32 v[48:49], v[0:1]
	v_mov_b64_e32 v[76:77], v[12:13]
	v_mov_b64_e32 v[74:75], v[10:11]
	v_mov_b64_e32 v[72:73], v[8:9]
	v_mov_b64_e32 v[70:71], v[6:7]
	v_mov_b64_e32 v[68:69], v[4:5]
	v_mov_b64_e32 v[66:67], v[2:3]
	v_mov_b64_e32 v[64:65], v[0:1]
	s_cmp_ge_u32 s33, 0x100
	s_cbranch_scc1 .Lmy_prio_a3
	s_setprio 1
